# only: prep_even sums of squares via DPP wave reduction
# baseline (speedup 1.0000x reference)
.LBB0_620:
	v_or_b32_e32 v25, s16, v178
	v_lshl_add_u32 v203, v25, 10, v179
	s_waitcnt lgkmcnt(0)
	ds_read2st64_b32 v[104:105], v203 offset1:4
	ds_read2st64_b32 v[106:107], v203 offset0:8 offset1:12
	ds_read2st64_b32 v[112:113], v203 offset0:40 offset1:44
	ds_read2st64_b32 v[116:117], v203 offset0:48 offset1:52
	ds_read2st64_b32 v[120:121], v203 offset0:56 offset1:60
	s_waitcnt lgkmcnt(4)
	v_lshlrev_b32_e32 v108, 16, v104
	v_and_b32_e32 v109, 0xffff0000, v104
	v_lshlrev_b32_e32 v160, 16, v105
	v_and_b32_e32 v161, 0xffff0000, v105
	v_pk_fma_f32 v[104:105], v[76:77], v[108:109], v[78:79]
	ds_read2st64_b32 v[108:109], v203 offset0:16 offset1:20
	s_waitcnt lgkmcnt(4)
	v_lshlrev_b32_e32 v164, 16, v106
	v_and_b32_e32 v165, 0xffff0000, v106
	v_lshlrev_b32_e32 v162, 16, v107
	v_and_b32_e32 v163, 0xffff0000, v107
	ds_read2st64_b32 v[106:107], v203 offset0:24 offset1:28
	v_pk_fma_f32 v[104:105], v[34:35], v[160:161], v[104:105]
	s_waitcnt lgkmcnt(1)
	v_lshlrev_b32_e32 v158, 16, v108
	v_pk_fma_f32 v[104:105], v[92:93], v[164:165], v[104:105]
	v_and_b32_e32 v159, 0xffff0000, v108
	v_lshlrev_b32_e32 v142, 16, v109
	v_and_b32_e32 v143, 0xffff0000, v109
	ds_read2st64_b32 v[108:109], v203 offset0:32 offset1:36
	v_pk_fma_f32 v[104:105], v[52:53], v[162:163], v[104:105]
	s_waitcnt lgkmcnt(1)
	v_lshlrev_b32_e32 v122, 16, v106
	v_pk_fma_f32 v[104:105], v[36:37], v[158:159], v[104:105]
	v_and_b32_e32 v123, 0xffff0000, v106
	v_pk_fma_f32 v[104:105], v[38:39], v[142:143], v[104:105]
	s_waitcnt lgkmcnt(0)
	v_lshlrev_b32_e32 v106, 16, v108
	v_pk_fma_f32 v[110:111], v[40:41], v[122:123], v[104:105]
	v_lshlrev_b32_e32 v104, 16, v107
	v_and_b32_e32 v105, 0xffff0000, v107
	v_pk_fma_f32 v[110:111], v[54:55], v[104:105], v[110:111]
	v_and_b32_e32 v107, 0xffff0000, v108
	v_pk_fma_f32 v[110:111], v[42:43], v[106:107], v[110:111]
	v_lshlrev_b32_e32 v108, 16, v109
	v_and_b32_e32 v109, 0xffff0000, v109
	v_pk_fma_f32 v[114:115], v[44:45], v[108:109], v[110:111]
	v_lshlrev_b32_e32 v110, 16, v112
	v_and_b32_e32 v111, 0xffff0000, v112
	v_pk_fma_f32 v[114:115], v[46:47], v[110:111], v[114:115]
	v_lshlrev_b32_e32 v112, 16, v113
	v_and_b32_e32 v113, 0xffff0000, v113
	ds_read2st64_b32 v[126:127], v203 offset0:64 offset1:68
	v_pk_fma_f32 v[118:119], v[56:57], v[112:113], v[114:115]
	v_lshlrev_b32_e32 v114, 16, v116
	v_and_b32_e32 v115, 0xffff0000, v116
	v_pk_fma_f32 v[118:119], v[48:49], v[114:115], v[118:119]
	v_lshlrev_b32_e32 v116, 16, v117
	v_and_b32_e32 v117, 0xffff0000, v117
	ds_read2st64_b32 v[130:131], v203 offset0:72 offset1:76
	v_pk_fma_f32 v[124:125], v[50:51], v[116:117], v[118:119]
	v_lshlrev_b32_e32 v118, 16, v120
	v_and_b32_e32 v119, 0xffff0000, v120
	v_pk_fma_f32 v[124:125], v[60:61], v[118:119], v[124:125]
	v_lshlrev_b32_e32 v120, 16, v121
	v_and_b32_e32 v121, 0xffff0000, v121
	ds_read2st64_b32 v[134:135], v203 offset0:80 offset1:84
	v_pk_fma_f32 v[128:129], v[58:59], v[120:121], v[124:125]
	s_waitcnt lgkmcnt(2)
	v_lshlrev_b32_e32 v124, 16, v126
	v_and_b32_e32 v125, 0xffff0000, v126
	v_pk_fma_f32 v[128:129], v[62:63], v[124:125], v[128:129]
	v_lshlrev_b32_e32 v126, 16, v127
	v_and_b32_e32 v127, 0xffff0000, v127
	ds_read2st64_b32 v[138:139], v203 offset0:88 offset1:92
	v_pk_fma_f32 v[132:133], v[64:65], v[126:127], v[128:129]
	s_waitcnt lgkmcnt(2)
	v_lshlrev_b32_e32 v128, 16, v130
	v_and_b32_e32 v129, 0xffff0000, v130
	v_pk_fma_f32 v[132:133], v[66:67], v[128:129], v[132:133]
	v_lshlrev_b32_e32 v130, 16, v131
	v_and_b32_e32 v131, 0xffff0000, v131
	ds_read2st64_b32 v[144:145], v203 offset0:96 offset1:100
	v_pk_fma_f32 v[136:137], v[84:85], v[130:131], v[132:133]
	s_waitcnt lgkmcnt(2)
	v_lshlrev_b32_e32 v132, 16, v134
	v_and_b32_e32 v133, 0xffff0000, v134
	v_pk_fma_f32 v[136:137], v[68:69], v[132:133], v[136:137]
	v_lshlrev_b32_e32 v134, 16, v135
	v_and_b32_e32 v135, 0xffff0000, v135
	ds_read2st64_b32 v[148:149], v203 offset0:104 offset1:108
	v_pk_fma_f32 v[140:141], v[70:71], v[134:135], v[136:137]
	s_waitcnt lgkmcnt(2)
	v_lshlrev_b32_e32 v136, 16, v138
	v_and_b32_e32 v137, 0xffff0000, v138
	v_pk_fma_f32 v[140:141], v[72:73], v[136:137], v[140:141]
	v_lshlrev_b32_e32 v138, 16, v139
	v_and_b32_e32 v139, 0xffff0000, v139
	ds_read2st64_b32 v[152:153], v203 offset0:112 offset1:116
	v_pk_fma_f32 v[146:147], v[86:87], v[138:139], v[140:141]
	s_waitcnt lgkmcnt(2)
	v_lshlrev_b32_e32 v140, 16, v144
	v_and_b32_e32 v141, 0xffff0000, v144
	v_pk_fma_f32 v[146:147], v[74:75], v[140:141], v[146:147]
	v_lshlrev_b32_e32 v144, 16, v145
	v_and_b32_e32 v145, 0xffff0000, v145
	ds_read2st64_b32 v[170:171], v203 offset0:120 offset1:124
	v_pk_fma_f32 v[150:151], v[82:83], v[144:145], v[146:147]
	s_waitcnt lgkmcnt(2)
	v_lshlrev_b32_e32 v146, 16, v148
	v_and_b32_e32 v147, 0xffff0000, v148
	v_pk_fma_f32 v[150:151], v[88:89], v[146:147], v[150:151]
	v_lshlrev_b32_e32 v148, 16, v149
	v_and_b32_e32 v149, 0xffff0000, v149
	v_pk_fma_f32 v[154:155], v[90:91], v[148:149], v[150:151]
	s_waitcnt lgkmcnt(1)
	v_lshlrev_b32_e32 v150, 16, v152
	v_and_b32_e32 v151, 0xffff0000, v152
	v_pk_fma_f32 v[154:155], v[94:95], v[150:151], v[154:155]
	v_lshlrev_b32_e32 v152, 16, v153
	v_and_b32_e32 v153, 0xffff0000, v153
	v_pk_fma_f32 v[156:157], v[96:97], v[152:153], v[154:155]
	s_waitcnt lgkmcnt(0)
	v_lshlrev_b32_e32 v154, 16, v170
	v_and_b32_e32 v155, 0xffff0000, v170
	v_pk_fma_f32 v[204:205], v[98:99], v[154:155], v[156:157]
	s_nop 0
	v_pk_mul_f32 v[156:157], v[204:205], v[204:205]
	s_nop 0
	v_add_f32_e32 v156, v156, v157
	s_waitcnt lgkmcnt(0)
	s_nop 1
	v_add_f32_dpp v156, v156, v156 quad_perm:[1,0,3,2] row_mask:0xf bank_mask:0xf
	s_nop 1
	v_add_f32_dpp v156, v156, v156 quad_perm:[2,3,0,1] row_mask:0xf bank_mask:0xf
	s_nop 1
	v_add_f32_dpp v156, v156, v156 row_ror:4 row_mask:0xf bank_mask:0xf
	s_nop 1
	v_add_f32_dpp v156, v156, v156 row_ror:8 row_mask:0xf bank_mask:0xf
	s_nop 1
	v_add_f32_dpp v156, v156, v156 row_bcast:15 row_mask:0xa bank_mask:0xf
	s_nop 1
	v_add_f32_dpp v156, v156, v156 row_bcast:31 row_mask:0xc bank_mask:0xf
	s_nop 1
	v_readlane_b32 s98, v156, 63
	ds_read2st64_b32 v[168:169], v203 offset0:128 offset1:132
	ds_read2st64_b32 v[166:167], v203 offset0:136 offset1:140
	ds_read2st64_b32 v[156:157], v203 offset0:144 offset1:148
	v_lshl_add_u32 v206, v25, 11, v180
	ds_write_b64 v206, v[204:205] offset:63488
	s_and_saveexec_b64 s[48:49], s[6:7]
	s_cbranch_execz .LBB0_622
	s_waitcnt lgkmcnt(1)
	v_mov_b32_e32 v170, s98
	v_lshl_add_u32 v203, v25, 4, s3
	ds_write_b32 v203, v170
.LBB0_622:
	s_or_b64 exec, exec, s[48:49]
	v_pk_fma_f32 v[160:161], v[76:77], v[160:161], v[78:79]
	s_nop 0
	v_pk_fma_f32 v[160:161], v[34:35], v[164:165], v[160:161]
	s_nop 0
	v_pk_fma_f32 v[160:161], v[92:93], v[162:163], v[160:161]
	s_nop 0
	v_pk_fma_f32 v[160:161], v[52:53], v[158:159], v[160:161]
	s_nop 0
	v_pk_fma_f32 v[160:161], v[36:37], v[142:143], v[160:161]
	s_nop 0
	v_pk_fma_f32 v[160:161], v[38:39], v[122:123], v[160:161]
	s_nop 0
	v_pk_fma_f32 v[160:161], v[40:41], v[104:105], v[160:161]
	s_nop 0
	v_pk_fma_f32 v[160:161], v[54:55], v[106:107], v[160:161]
	s_nop 0
	v_pk_fma_f32 v[160:161], v[42:43], v[108:109], v[160:161]
	s_nop 0
	v_pk_fma_f32 v[160:161], v[44:45], v[110:111], v[160:161]
	s_nop 0
	v_pk_fma_f32 v[160:161], v[46:47], v[112:113], v[160:161]
	s_nop 0
	v_pk_fma_f32 v[160:161], v[56:57], v[114:115], v[160:161]
	s_nop 0
	v_pk_fma_f32 v[160:161], v[48:49], v[116:117], v[160:161]
	s_nop 0
	v_pk_fma_f32 v[160:161], v[50:51], v[118:119], v[160:161]
	s_nop 0
	v_pk_fma_f32 v[160:161], v[60:61], v[120:121], v[160:161]
	s_nop 0
	v_pk_fma_f32 v[160:161], v[58:59], v[124:125], v[160:161]
	s_nop 0
	v_pk_fma_f32 v[160:161], v[62:63], v[126:127], v[160:161]
	s_nop 0
	v_pk_fma_f32 v[160:161], v[64:65], v[128:129], v[160:161]
	s_nop 0
	v_pk_fma_f32 v[160:161], v[66:67], v[130:131], v[160:161]
	s_nop 0
	v_pk_fma_f32 v[160:161], v[84:85], v[132:133], v[160:161]
	s_nop 0
	v_pk_fma_f32 v[160:161], v[68:69], v[134:135], v[160:161]
	s_nop 0
	v_pk_fma_f32 v[160:161], v[70:71], v[136:137], v[160:161]
	s_nop 0
	v_pk_fma_f32 v[160:161], v[72:73], v[138:139], v[160:161]
	s_nop 0
	v_pk_fma_f32 v[160:161], v[86:87], v[140:141], v[160:161]
	s_nop 0
	v_pk_fma_f32 v[160:161], v[74:75], v[144:145], v[160:161]
	s_nop 0
	v_pk_fma_f32 v[160:161], v[82:83], v[146:147], v[160:161]
	s_nop 0
	v_pk_fma_f32 v[160:161], v[88:89], v[148:149], v[160:161]
	s_nop 0
	v_pk_fma_f32 v[160:161], v[90:91], v[150:151], v[160:161]
	s_nop 0
	v_pk_fma_f32 v[160:161], v[94:95], v[152:153], v[160:161]
	s_nop 0
	v_pk_fma_f32 v[204:205], v[96:97], v[154:155], v[160:161]
	v_lshlrev_b32_e32 v160, 16, v171
	v_and_b32_e32 v161, 0xffff0000, v171
	v_pk_fma_f32 v[204:205], v[98:99], v[160:161], v[204:205]
	s_nop 0
	v_pk_mul_f32 v[170:171], v[204:205], v[204:205]
	s_nop 0
	v_add_f32_e32 v170, v170, v171
	s_waitcnt lgkmcnt(0)
	s_nop 1
	v_add_f32_dpp v170, v170, v170 quad_perm:[1,0,3,2] row_mask:0xf bank_mask:0xf
	s_nop 1
	v_add_f32_dpp v170, v170, v170 quad_perm:[2,3,0,1] row_mask:0xf bank_mask:0xf
	s_nop 1
	v_add_f32_dpp v170, v170, v170 row_ror:4 row_mask:0xf bank_mask:0xf
	s_nop 1
	v_add_f32_dpp v170, v170, v170 row_ror:8 row_mask:0xf bank_mask:0xf
	s_nop 1
	v_add_f32_dpp v170, v170, v170 row_bcast:15 row_mask:0xa bank_mask:0xf
	s_nop 1
	v_add_f32_dpp v170, v170, v170 row_bcast:31 row_mask:0xc bank_mask:0xf
	s_nop 1
	v_readlane_b32 s98, v170, 63
	v_or_b32_e32 v171, 1, v25
	v_lshl_add_u32 v206, v171, 11, v180
	ds_write_b64 v206, v[204:205] offset:63488
	s_and_saveexec_b64 s[48:49], s[6:7]
	s_cbranch_execz .LBB0_624
	s_waitcnt lgkmcnt(1)
	v_mov_b32_e32 v170, s98
	v_lshl_add_u32 v171, v171, 4, s3
	ds_write_b32 v171, v170
.LBB0_624:
	s_or_b64 exec, exec, s[48:49]
	v_pk_fma_f32 v[164:165], v[76:77], v[164:165], v[78:79]
	s_nop 0
	v_pk_fma_f32 v[164:165], v[34:35], v[162:163], v[164:165]
	s_nop 0
	v_pk_fma_f32 v[164:165], v[92:93], v[158:159], v[164:165]
	s_nop 0
	v_pk_fma_f32 v[164:165], v[52:53], v[142:143], v[164:165]
	s_nop 0
	v_pk_fma_f32 v[164:165], v[36:37], v[122:123], v[164:165]
	s_nop 0
	v_pk_fma_f32 v[164:165], v[38:39], v[104:105], v[164:165]
	s_nop 0
	v_pk_fma_f32 v[164:165], v[40:41], v[106:107], v[164:165]
	s_nop 0
	v_pk_fma_f32 v[164:165], v[54:55], v[108:109], v[164:165]
	s_nop 0
	v_pk_fma_f32 v[164:165], v[42:43], v[110:111], v[164:165]
	s_nop 0
	v_pk_fma_f32 v[164:165], v[44:45], v[112:113], v[164:165]
	s_nop 0
	v_pk_fma_f32 v[164:165], v[46:47], v[114:115], v[164:165]
	s_nop 0
	v_pk_fma_f32 v[164:165], v[56:57], v[116:117], v[164:165]
	s_nop 0
	v_pk_fma_f32 v[164:165], v[48:49], v[118:119], v[164:165]
	s_nop 0
	v_pk_fma_f32 v[164:165], v[50:51], v[120:121], v[164:165]
	s_nop 0
	v_pk_fma_f32 v[164:165], v[60:61], v[124:125], v[164:165]
	s_nop 0
	v_pk_fma_f32 v[164:165], v[58:59], v[126:127], v[164:165]
	s_nop 0
	v_pk_fma_f32 v[164:165], v[62:63], v[128:129], v[164:165]
	s_nop 0
	v_pk_fma_f32 v[164:165], v[64:65], v[130:131], v[164:165]
	s_nop 0
	v_pk_fma_f32 v[164:165], v[66:67], v[132:133], v[164:165]
	s_nop 0
	v_pk_fma_f32 v[164:165], v[84:85], v[134:135], v[164:165]
	s_nop 0
	v_pk_fma_f32 v[164:165], v[68:69], v[136:137], v[164:165]
	s_nop 0
	v_pk_fma_f32 v[164:165], v[70:71], v[138:139], v[164:165]
	s_nop 0
	v_pk_fma_f32 v[164:165], v[72:73], v[140:141], v[164:165]
	s_nop 0
	v_pk_fma_f32 v[164:165], v[86:87], v[144:145], v[164:165]
	s_nop 0
	v_pk_fma_f32 v[164:165], v[74:75], v[146:147], v[164:165]
	s_nop 0
	v_pk_fma_f32 v[164:165], v[82:83], v[148:149], v[164:165]
	s_nop 0
	v_pk_fma_f32 v[164:165], v[88:89], v[150:151], v[164:165]
	s_nop 0
	v_pk_fma_f32 v[164:165], v[90:91], v[152:153], v[164:165]
	s_nop 0
	v_pk_fma_f32 v[164:165], v[94:95], v[154:155], v[164:165]
	s_nop 0
	v_pk_fma_f32 v[170:171], v[96:97], v[160:161], v[164:165]
	v_lshlrev_b32_e32 v164, 16, v168
	v_and_b32_e32 v165, 0xffff0000, v168
	v_pk_fma_f32 v[204:205], v[98:99], v[164:165], v[170:171]
	s_nop 0
	v_pk_mul_f32 v[170:171], v[204:205], v[204:205]
	s_nop 0
	v_add_f32_e32 v168, v170, v171
	s_waitcnt lgkmcnt(0)
	s_nop 1
	v_add_f32_dpp v168, v168, v168 quad_perm:[1,0,3,2] row_mask:0xf bank_mask:0xf
	s_nop 1
	v_add_f32_dpp v168, v168, v168 quad_perm:[2,3,0,1] row_mask:0xf bank_mask:0xf
	s_nop 1
	v_add_f32_dpp v168, v168, v168 row_ror:4 row_mask:0xf bank_mask:0xf
	s_nop 1
	v_add_f32_dpp v168, v168, v168 row_ror:8 row_mask:0xf bank_mask:0xf
	s_nop 1
	v_add_f32_dpp v168, v168, v168 row_bcast:15 row_mask:0xa bank_mask:0xf
	s_nop 1
	v_add_f32_dpp v168, v168, v168 row_bcast:31 row_mask:0xc bank_mask:0xf
	s_nop 1
	v_readlane_b32 s98, v168, 63
	v_or_b32_e32 v170, 2, v25
	v_lshl_add_u32 v203, v170, 11, v180
	ds_write_b64 v203, v[204:205] offset:63488
	s_and_saveexec_b64 s[48:49], s[6:7]
	s_cbranch_execz .LBB0_626
	s_waitcnt lgkmcnt(1)
	v_mov_b32_e32 v168, s98
	v_lshl_add_u32 v170, v170, 4, s3
	ds_write_b32 v170, v168
.LBB0_626:
	s_or_b64 exec, exec, s[48:49]
	v_pk_fma_f32 v[162:163], v[76:77], v[162:163], v[78:79]
	s_nop 0
	v_pk_fma_f32 v[162:163], v[34:35], v[158:159], v[162:163]
	s_nop 0
	v_pk_fma_f32 v[162:163], v[92:93], v[142:143], v[162:163]
	s_nop 0
	v_pk_fma_f32 v[162:163], v[52:53], v[122:123], v[162:163]
	s_nop 0
	v_pk_fma_f32 v[162:163], v[36:37], v[104:105], v[162:163]
	s_nop 0
	v_pk_fma_f32 v[162:163], v[38:39], v[106:107], v[162:163]
	s_nop 0
	v_pk_fma_f32 v[162:163], v[40:41], v[108:109], v[162:163]
	s_nop 0
	v_pk_fma_f32 v[162:163], v[54:55], v[110:111], v[162:163]
	s_nop 0
	v_pk_fma_f32 v[162:163], v[42:43], v[112:113], v[162:163]
	s_nop 0
	v_pk_fma_f32 v[162:163], v[44:45], v[114:115], v[162:163]
	s_nop 0
	v_pk_fma_f32 v[162:163], v[46:47], v[116:117], v[162:163]
	s_nop 0
	v_pk_fma_f32 v[162:163], v[56:57], v[118:119], v[162:163]
	s_nop 0
	v_pk_fma_f32 v[162:163], v[48:49], v[120:121], v[162:163]
	s_nop 0
	v_pk_fma_f32 v[162:163], v[50:51], v[124:125], v[162:163]
	s_nop 0
	v_pk_fma_f32 v[162:163], v[60:61], v[126:127], v[162:163]
	s_nop 0
	v_pk_fma_f32 v[162:163], v[58:59], v[128:129], v[162:163]
	s_nop 0
	v_pk_fma_f32 v[162:163], v[62:63], v[130:131], v[162:163]
	s_nop 0
	v_pk_fma_f32 v[162:163], v[64:65], v[132:133], v[162:163]
	s_nop 0
	v_pk_fma_f32 v[162:163], v[66:67], v[134:135], v[162:163]
	s_nop 0
	v_pk_fma_f32 v[162:163], v[84:85], v[136:137], v[162:163]
	s_nop 0
	v_pk_fma_f32 v[162:163], v[68:69], v[138:139], v[162:163]
	s_nop 0
	v_pk_fma_f32 v[162:163], v[70:71], v[140:141], v[162:163]
	s_nop 0
	v_pk_fma_f32 v[162:163], v[72:73], v[144:145], v[162:163]
	s_nop 0
	v_pk_fma_f32 v[162:163], v[86:87], v[146:147], v[162:163]
	s_nop 0
	v_pk_fma_f32 v[162:163], v[74:75], v[148:149], v[162:163]
	s_nop 0
	v_pk_fma_f32 v[162:163], v[82:83], v[150:151], v[162:163]
	s_nop 0
	v_pk_fma_f32 v[162:163], v[88:89], v[152:153], v[162:163]
	s_nop 0
	v_pk_fma_f32 v[162:163], v[90:91], v[154:155], v[162:163]
	s_nop 0
	v_pk_fma_f32 v[162:163], v[94:95], v[160:161], v[162:163]
	s_waitcnt lgkmcnt(1)
	v_pk_fma_f32 v[170:171], v[96:97], v[164:165], v[162:163]
	v_lshlrev_b32_e32 v162, 16, v169
	v_and_b32_e32 v163, 0xffff0000, v169
	v_pk_fma_f32 v[204:205], v[98:99], v[162:163], v[170:171]
	s_nop 0
	v_pk_mul_f32 v[168:169], v[204:205], v[204:205]
	s_nop 0
	v_add_f32_e32 v168, v168, v169
	s_waitcnt lgkmcnt(0)
	s_nop 1
	v_add_f32_dpp v168, v168, v168 quad_perm:[1,0,3,2] row_mask:0xf bank_mask:0xf
	s_nop 1
	v_add_f32_dpp v168, v168, v168 quad_perm:[2,3,0,1] row_mask:0xf bank_mask:0xf
	s_nop 1
	v_add_f32_dpp v168, v168, v168 row_ror:4 row_mask:0xf bank_mask:0xf
	s_nop 1
	v_add_f32_dpp v168, v168, v168 row_ror:8 row_mask:0xf bank_mask:0xf
	s_nop 1
	v_add_f32_dpp v168, v168, v168 row_bcast:15 row_mask:0xa bank_mask:0xf
	s_nop 1
	v_add_f32_dpp v168, v168, v168 row_bcast:31 row_mask:0xc bank_mask:0xf
	s_nop 1
	v_readlane_b32 s98, v168, 63
	v_or_b32_e32 v169, 3, v25
	v_lshl_add_u32 v171, v169, 11, v180
	ds_write_b64 v171, v[204:205] offset:63488
	s_and_saveexec_b64 s[48:49], s[6:7]
	s_cbranch_execz .LBB0_628
	s_waitcnt lgkmcnt(1)
	v_mov_b32_e32 v168, s98
	v_lshl_add_u32 v169, v169, 4, s3
	ds_write_b32 v169, v168
.LBB0_628:
	s_or_b64 exec, exec, s[48:49]
	v_pk_fma_f32 v[158:159], v[76:77], v[158:159], v[78:79]
	s_nop 0
	v_pk_fma_f32 v[158:159], v[34:35], v[142:143], v[158:159]
	s_nop 0
	v_pk_fma_f32 v[158:159], v[92:93], v[122:123], v[158:159]
	s_nop 0
	v_pk_fma_f32 v[158:159], v[52:53], v[104:105], v[158:159]
	s_nop 0
	v_pk_fma_f32 v[158:159], v[36:37], v[106:107], v[158:159]
	s_nop 0
	v_pk_fma_f32 v[158:159], v[38:39], v[108:109], v[158:159]
	s_nop 0
	v_pk_fma_f32 v[158:159], v[40:41], v[110:111], v[158:159]
	s_nop 0
	v_pk_fma_f32 v[158:159], v[54:55], v[112:113], v[158:159]
	s_nop 0
	v_pk_fma_f32 v[158:159], v[42:43], v[114:115], v[158:159]
	s_nop 0
	v_pk_fma_f32 v[158:159], v[44:45], v[116:117], v[158:159]
	s_nop 0
	v_pk_fma_f32 v[158:159], v[46:47], v[118:119], v[158:159]
	s_nop 0
	v_pk_fma_f32 v[158:159], v[56:57], v[120:121], v[158:159]
	s_nop 0
	v_pk_fma_f32 v[158:159], v[48:49], v[124:125], v[158:159]
	s_nop 0
	v_pk_fma_f32 v[158:159], v[50:51], v[126:127], v[158:159]
	s_nop 0
	v_pk_fma_f32 v[158:159], v[60:61], v[128:129], v[158:159]
	s_nop 0
	v_pk_fma_f32 v[158:159], v[58:59], v[130:131], v[158:159]
	s_nop 0
	v_pk_fma_f32 v[158:159], v[62:63], v[132:133], v[158:159]
	s_nop 0
	v_pk_fma_f32 v[158:159], v[64:65], v[134:135], v[158:159]
	s_nop 0
	v_pk_fma_f32 v[158:159], v[66:67], v[136:137], v[158:159]
	s_nop 0
	v_pk_fma_f32 v[158:159], v[84:85], v[138:139], v[158:159]
	s_nop 0
	v_pk_fma_f32 v[158:159], v[68:69], v[140:141], v[158:159]
	s_nop 0
	v_pk_fma_f32 v[158:159], v[70:71], v[144:145], v[158:159]
	s_nop 0
	v_pk_fma_f32 v[158:159], v[72:73], v[146:147], v[158:159]
	s_nop 0
	v_pk_fma_f32 v[158:159], v[86:87], v[148:149], v[158:159]
	s_nop 0
	v_pk_fma_f32 v[158:159], v[74:75], v[150:151], v[158:159]
	s_nop 0
	v_pk_fma_f32 v[158:159], v[82:83], v[152:153], v[158:159]
	s_nop 0
	v_pk_fma_f32 v[158:159], v[88:89], v[154:155], v[158:159]
	s_nop 0
	v_pk_fma_f32 v[158:159], v[90:91], v[160:161], v[158:159]
	s_nop 0
	v_pk_fma_f32 v[158:159], v[94:95], v[164:165], v[158:159]
	s_nop 0
	v_pk_fma_f32 v[168:169], v[96:97], v[162:163], v[158:159]
	v_lshlrev_b32_e32 v158, 16, v166
	v_and_b32_e32 v159, 0xffff0000, v166
	s_waitcnt lgkmcnt(1)
	v_pk_fma_f32 v[170:171], v[98:99], v[158:159], v[168:169]
	s_nop 0
	v_pk_mul_f32 v[168:169], v[170:171], v[170:171]
	s_nop 0
	v_add_f32_e32 v166, v168, v169
	s_waitcnt lgkmcnt(0)
	s_nop 1
	v_add_f32_dpp v166, v166, v166 quad_perm:[1,0,3,2] row_mask:0xf bank_mask:0xf
	s_nop 1
	v_add_f32_dpp v166, v166, v166 quad_perm:[2,3,0,1] row_mask:0xf bank_mask:0xf
	s_nop 1
	v_add_f32_dpp v166, v166, v166 row_ror:4 row_mask:0xf bank_mask:0xf
	s_nop 1
	v_add_f32_dpp v166, v166, v166 row_ror:8 row_mask:0xf bank_mask:0xf
	s_nop 1
	v_add_f32_dpp v166, v166, v166 row_bcast:15 row_mask:0xa bank_mask:0xf
	s_nop 1
	v_add_f32_dpp v166, v166, v166 row_bcast:31 row_mask:0xc bank_mask:0xf
	s_nop 1
	v_readlane_b32 s98, v166, 63
	v_or_b32_e32 v168, 4, v25
	v_lshl_add_u32 v203, v168, 11, v180
	ds_write_b64 v203, v[170:171] offset:63488
	s_and_saveexec_b64 s[48:49], s[6:7]
	s_cbranch_execz .LBB0_630
	s_waitcnt lgkmcnt(1)
	v_mov_b32_e32 v166, s98
	v_lshl_add_u32 v168, v168, 4, s3
	ds_write_b32 v168, v166
.LBB0_630:
	s_or_b64 exec, exec, s[48:49]
	v_pk_fma_f32 v[142:143], v[76:77], v[142:143], v[78:79]
	s_nop 0
	v_pk_fma_f32 v[142:143], v[34:35], v[122:123], v[142:143]
	s_nop 0
	v_pk_fma_f32 v[142:143], v[92:93], v[104:105], v[142:143]
	s_nop 0
	v_pk_fma_f32 v[142:143], v[52:53], v[106:107], v[142:143]
	s_nop 0
	v_pk_fma_f32 v[142:143], v[36:37], v[108:109], v[142:143]
	s_nop 0
	v_pk_fma_f32 v[142:143], v[38:39], v[110:111], v[142:143]
	s_nop 0
	v_pk_fma_f32 v[142:143], v[40:41], v[112:113], v[142:143]
	s_nop 0
	v_pk_fma_f32 v[142:143], v[54:55], v[114:115], v[142:143]
	s_nop 0
	v_pk_fma_f32 v[142:143], v[42:43], v[116:117], v[142:143]
	s_nop 0
	v_pk_fma_f32 v[142:143], v[44:45], v[118:119], v[142:143]
	s_nop 0
	v_pk_fma_f32 v[142:143], v[46:47], v[120:121], v[142:143]
	s_nop 0
	v_pk_fma_f32 v[142:143], v[56:57], v[124:125], v[142:143]
	s_nop 0
	v_pk_fma_f32 v[142:143], v[48:49], v[126:127], v[142:143]
	s_nop 0
	v_pk_fma_f32 v[142:143], v[50:51], v[128:129], v[142:143]
	s_nop 0
	v_pk_fma_f32 v[142:143], v[60:61], v[130:131], v[142:143]
	s_nop 0
	v_pk_fma_f32 v[142:143], v[58:59], v[132:133], v[142:143]
	s_nop 0
	v_pk_fma_f32 v[142:143], v[62:63], v[134:135], v[142:143]
	s_nop 0
	v_pk_fma_f32 v[142:143], v[64:65], v[136:137], v[142:143]
	s_nop 0
	v_pk_fma_f32 v[142:143], v[66:67], v[138:139], v[142:143]
	s_nop 0
	v_pk_fma_f32 v[142:143], v[84:85], v[140:141], v[142:143]
	s_nop 0
	v_pk_fma_f32 v[142:143], v[68:69], v[144:145], v[142:143]
	s_nop 0
	v_pk_fma_f32 v[142:143], v[70:71], v[146:147], v[142:143]
	s_nop 0
	v_pk_fma_f32 v[142:143], v[72:73], v[148:149], v[142:143]
	s_nop 0
	v_pk_fma_f32 v[142:143], v[86:87], v[150:151], v[142:143]
	s_nop 0
	v_pk_fma_f32 v[142:143], v[74:75], v[152:153], v[142:143]
	s_nop 0
	v_pk_fma_f32 v[142:143], v[82:83], v[154:155], v[142:143]
	s_nop 0
	v_pk_fma_f32 v[142:143], v[88:89], v[160:161], v[142:143]
	s_nop 0
	v_pk_fma_f32 v[142:143], v[90:91], v[164:165], v[142:143]
	s_nop 0
	v_pk_fma_f32 v[142:143], v[94:95], v[162:163], v[142:143]
	s_waitcnt lgkmcnt(1)
	v_pk_fma_f32 v[168:169], v[96:97], v[158:159], v[142:143]
	v_lshlrev_b32_e32 v142, 16, v167
	v_and_b32_e32 v143, 0xffff0000, v167
	v_pk_fma_f32 v[170:171], v[98:99], v[142:143], v[168:169]
	s_nop 0
	v_pk_mul_f32 v[166:167], v[170:171], v[170:171]
	s_nop 0
	v_add_f32_e32 v166, v166, v167
	s_waitcnt lgkmcnt(0)
	s_nop 1
	v_add_f32_dpp v166, v166, v166 quad_perm:[1,0,3,2] row_mask:0xf bank_mask:0xf
	s_nop 1
	v_add_f32_dpp v166, v166, v166 quad_perm:[2,3,0,1] row_mask:0xf bank_mask:0xf
	s_nop 1
	v_add_f32_dpp v166, v166, v166 row_ror:4 row_mask:0xf bank_mask:0xf
	s_nop 1
	v_add_f32_dpp v166, v166, v166 row_ror:8 row_mask:0xf bank_mask:0xf
	s_nop 1
	v_add_f32_dpp v166, v166, v166 row_bcast:15 row_mask:0xa bank_mask:0xf
	s_nop 1
	v_add_f32_dpp v166, v166, v166 row_bcast:31 row_mask:0xc bank_mask:0xf
	s_nop 1
	v_readlane_b32 s98, v166, 63
	v_or_b32_e32 v167, 5, v25
	v_lshl_add_u32 v169, v167, 11, v180
	ds_write_b64 v169, v[170:171] offset:63488
	s_and_saveexec_b64 s[48:49], s[6:7]
	s_cbranch_execz .LBB0_632
	s_waitcnt lgkmcnt(1)
	v_mov_b32_e32 v166, s98
	v_lshl_add_u32 v167, v167, 4, s3
	ds_write_b32 v167, v166
.LBB0_632:
	s_or_b64 exec, exec, s[48:49]
	v_pk_fma_f32 v[122:123], v[76:77], v[122:123], v[78:79]
	s_nop 0
	v_pk_fma_f32 v[122:123], v[34:35], v[104:105], v[122:123]
	s_nop 0
	v_pk_fma_f32 v[122:123], v[92:93], v[106:107], v[122:123]
	s_nop 0
	v_pk_fma_f32 v[122:123], v[52:53], v[108:109], v[122:123]
	s_nop 0
	v_pk_fma_f32 v[122:123], v[36:37], v[110:111], v[122:123]
	s_nop 0
	v_pk_fma_f32 v[122:123], v[38:39], v[112:113], v[122:123]
	s_nop 0
	v_pk_fma_f32 v[122:123], v[40:41], v[114:115], v[122:123]
	s_nop 0
	v_pk_fma_f32 v[122:123], v[54:55], v[116:117], v[122:123]
	s_nop 0
	v_pk_fma_f32 v[122:123], v[42:43], v[118:119], v[122:123]
	s_nop 0
	v_pk_fma_f32 v[122:123], v[44:45], v[120:121], v[122:123]
	s_nop 0
	v_pk_fma_f32 v[122:123], v[46:47], v[124:125], v[122:123]
	s_nop 0
	v_pk_fma_f32 v[122:123], v[56:57], v[126:127], v[122:123]
	s_nop 0
	v_pk_fma_f32 v[122:123], v[48:49], v[128:129], v[122:123]
	s_nop 0
	v_pk_fma_f32 v[122:123], v[50:51], v[130:131], v[122:123]
	s_nop 0
	v_pk_fma_f32 v[122:123], v[60:61], v[132:133], v[122:123]
	s_nop 0
	v_pk_fma_f32 v[122:123], v[58:59], v[134:135], v[122:123]
	s_nop 0
	v_pk_fma_f32 v[122:123], v[62:63], v[136:137], v[122:123]
	s_nop 0
	v_pk_fma_f32 v[122:123], v[64:65], v[138:139], v[122:123]
	s_nop 0
	v_pk_fma_f32 v[122:123], v[66:67], v[140:141], v[122:123]
	s_nop 0
	v_pk_fma_f32 v[122:123], v[84:85], v[144:145], v[122:123]
	s_nop 0
	v_pk_fma_f32 v[122:123], v[68:69], v[146:147], v[122:123]
	s_nop 0
	v_pk_fma_f32 v[122:123], v[70:71], v[148:149], v[122:123]
	s_nop 0
	v_pk_fma_f32 v[122:123], v[72:73], v[150:151], v[122:123]
	s_nop 0
	v_pk_fma_f32 v[122:123], v[86:87], v[152:153], v[122:123]
	s_nop 0
	v_pk_fma_f32 v[122:123], v[74:75], v[154:155], v[122:123]
	s_nop 0
	v_pk_fma_f32 v[122:123], v[82:83], v[160:161], v[122:123]
	s_nop 0
	v_pk_fma_f32 v[122:123], v[88:89], v[164:165], v[122:123]
	s_nop 0
	v_pk_fma_f32 v[122:123], v[90:91], v[162:163], v[122:123]
	s_nop 0
	v_pk_fma_f32 v[122:123], v[94:95], v[158:159], v[122:123]
	s_nop 0
	v_pk_fma_f32 v[166:167], v[96:97], v[142:143], v[122:123]
	v_lshlrev_b32_e32 v122, 16, v156
	v_and_b32_e32 v123, 0xffff0000, v156
	s_waitcnt lgkmcnt(1)
	v_pk_fma_f32 v[168:169], v[98:99], v[122:123], v[166:167]
	s_nop 0
	v_pk_mul_f32 v[166:167], v[168:169], v[168:169]
	s_nop 0
	v_add_f32_e32 v156, v166, v167
	s_waitcnt lgkmcnt(0)
	s_nop 1
	v_add_f32_dpp v156, v156, v156 quad_perm:[1,0,3,2] row_mask:0xf bank_mask:0xf
	s_nop 1
	v_add_f32_dpp v156, v156, v156 quad_perm:[2,3,0,1] row_mask:0xf bank_mask:0xf
	s_nop 1
	v_add_f32_dpp v156, v156, v156 row_ror:4 row_mask:0xf bank_mask:0xf
	s_nop 1
	v_add_f32_dpp v156, v156, v156 row_ror:8 row_mask:0xf bank_mask:0xf
	s_nop 1
	v_add_f32_dpp v156, v156, v156 row_bcast:15 row_mask:0xa bank_mask:0xf
	s_nop 1
	v_add_f32_dpp v156, v156, v156 row_bcast:31 row_mask:0xc bank_mask:0xf
	s_nop 1
	v_readlane_b32 s98, v156, 63
	v_or_b32_e32 v166, 6, v25
	v_lshl_add_u32 v170, v166, 11, v180
	ds_write_b64 v170, v[168:169] offset:63488
	s_and_saveexec_b64 s[48:49], s[6:7]
	s_cbranch_execz .LBB0_634
	s_waitcnt lgkmcnt(1)
	v_mov_b32_e32 v156, s98
	v_lshl_add_u32 v166, v166, 4, s3
	ds_write_b32 v166, v156
.LBB0_634:
	s_or_b64 exec, exec, s[48:49]
	v_pk_fma_f32 v[104:105], v[76:77], v[104:105], v[78:79]
	v_or_b32_e32 v25, 7, v25
	v_pk_fma_f32 v[104:105], v[34:35], v[106:107], v[104:105]
	v_lshlrev_b32_e32 v106, 16, v157
	v_pk_fma_f32 v[104:105], v[92:93], v[108:109], v[104:105]
	v_and_b32_e32 v107, 0xffff0000, v157
	v_pk_fma_f32 v[104:105], v[52:53], v[110:111], v[104:105]
	v_lshl_add_u32 v108, v25, 11, v180
	v_pk_fma_f32 v[104:105], v[36:37], v[112:113], v[104:105]
	s_nop 0
	v_pk_fma_f32 v[104:105], v[38:39], v[114:115], v[104:105]
	s_nop 0
	v_pk_fma_f32 v[104:105], v[40:41], v[116:117], v[104:105]
	s_nop 0
	v_pk_fma_f32 v[104:105], v[54:55], v[118:119], v[104:105]
	s_nop 0
	v_pk_fma_f32 v[104:105], v[42:43], v[120:121], v[104:105]
	s_nop 0
	v_pk_fma_f32 v[104:105], v[44:45], v[124:125], v[104:105]
	s_nop 0
	v_pk_fma_f32 v[104:105], v[46:47], v[126:127], v[104:105]
	s_nop 0
	v_pk_fma_f32 v[104:105], v[56:57], v[128:129], v[104:105]
	s_nop 0
	v_pk_fma_f32 v[104:105], v[48:49], v[130:131], v[104:105]
	s_nop 0
	v_pk_fma_f32 v[104:105], v[50:51], v[132:133], v[104:105]
	s_nop 0
	v_pk_fma_f32 v[104:105], v[60:61], v[134:135], v[104:105]
	s_nop 0
	v_pk_fma_f32 v[104:105], v[58:59], v[136:137], v[104:105]
	s_nop 0
	v_pk_fma_f32 v[104:105], v[62:63], v[138:139], v[104:105]
	s_nop 0
	v_pk_fma_f32 v[104:105], v[64:65], v[140:141], v[104:105]
	s_nop 0
	v_pk_fma_f32 v[104:105], v[66:67], v[144:145], v[104:105]
	s_nop 0
	v_pk_fma_f32 v[104:105], v[84:85], v[146:147], v[104:105]
	s_nop 0
	v_pk_fma_f32 v[104:105], v[68:69], v[148:149], v[104:105]
	s_nop 0
	v_pk_fma_f32 v[104:105], v[70:71], v[150:151], v[104:105]
	s_nop 0
	v_pk_fma_f32 v[104:105], v[72:73], v[152:153], v[104:105]
	s_nop 0
	v_pk_fma_f32 v[104:105], v[86:87], v[154:155], v[104:105]
	s_nop 0
	v_pk_fma_f32 v[104:105], v[74:75], v[160:161], v[104:105]
	s_nop 0
	v_pk_fma_f32 v[104:105], v[82:83], v[164:165], v[104:105]
	s_nop 0
	v_pk_fma_f32 v[104:105], v[88:89], v[162:163], v[104:105]
	s_nop 0
	v_pk_fma_f32 v[104:105], v[90:91], v[158:159], v[104:105]
	s_nop 0
	v_pk_fma_f32 v[104:105], v[94:95], v[142:143], v[104:105]
	s_nop 0
	v_pk_fma_f32 v[104:105], v[96:97], v[122:123], v[104:105]
	s_nop 0
	v_pk_fma_f32 v[106:107], v[98:99], v[106:107], v[104:105]
	ds_write_b64 v108, v[106:107] offset:63488
	v_pk_mul_f32 v[104:105], v[106:107], v[106:107]
	s_nop 0
	v_add_f32_e32 v104, v104, v105
	s_waitcnt lgkmcnt(0)
	s_nop 1
	v_add_f32_dpp v104, v104, v104 quad_perm:[1,0,3,2] row_mask:0xf bank_mask:0xf
	s_nop 1
	v_add_f32_dpp v104, v104, v104 quad_perm:[2,3,0,1] row_mask:0xf bank_mask:0xf
	s_nop 1
	v_add_f32_dpp v104, v104, v104 row_ror:4 row_mask:0xf bank_mask:0xf
	s_nop 1
	v_add_f32_dpp v104, v104, v104 row_ror:8 row_mask:0xf bank_mask:0xf
	s_nop 1
	v_add_f32_dpp v104, v104, v104 row_bcast:15 row_mask:0xa bank_mask:0xf
	s_nop 1
	v_add_f32_dpp v104, v104, v104 row_bcast:31 row_mask:0xc bank_mask:0xf
	s_nop 1
	v_readlane_b32 s98, v104, 63
	s_and_saveexec_b64 s[48:49], s[6:7]
	s_cbranch_execz .LBB0_619
	s_waitcnt lgkmcnt(0)
	v_mov_b32_e32 v104, s98
	v_lshl_add_u32 v25, v25, 4, s3
	ds_write_b32 v25, v104
	s_branch .LBB0_619

	.amdhsa_kernel _Z9trunk_fwd4Args
		.amdhsa_group_segment_fixed_size 0
		.amdhsa_private_segment_fixed_size 0
		.amdhsa_kernarg_size 448
		.amdhsa_user_sgpr_count 2
		.amdhsa_user_sgpr_dispatch_ptr 0
		.amdhsa_user_sgpr_queue_ptr 0
		.amdhsa_user_sgpr_kernarg_segment_ptr 1
		.amdhsa_user_sgpr_dispatch_id 0
		.amdhsa_user_sgpr_kernarg_preload_length 0
		.amdhsa_user_sgpr_kernarg_preload_offset 0
		.amdhsa_user_sgpr_private_segment_size 0
		.amdhsa_uses_dynamic_stack 0
		.amdhsa_enable_private_segment 0
		.amdhsa_system_sgpr_workgroup_id_x 1
		.amdhsa_system_sgpr_workgroup_id_y 0
		.amdhsa_system_sgpr_workgroup_id_z 0
		.amdhsa_system_sgpr_workgroup_info 0
		.amdhsa_system_vgpr_workitem_id 2
		.amdhsa_next_free_vgpr 255
		.amdhsa_next_free_sgpr 102
		.amdhsa_accum_offset 256
		.amdhsa_reserve_vcc 1
		.amdhsa_float_round_mode_32 0
		.amdhsa_float_round_mode_16_64 0
		.amdhsa_float_denorm_mode_32 3
		.amdhsa_float_denorm_mode_16_64 3
		.amdhsa_dx10_clamp 1
		.amdhsa_ieee_mode 1
		.amdhsa_fp16_overflow 0
		.amdhsa_tg_split 0
		.amdhsa_exception_fp_ieee_invalid_op 0
		.amdhsa_exception_fp_denorm_src 0
		.amdhsa_exception_fp_ieee_div_zero 0
		.amdhsa_exception_fp_ieee_overflow 0
		.amdhsa_exception_fp_ieee_underflow 0
		.amdhsa_exception_fp_ieee_inexact 0
		.amdhsa_exception_int_div_zero 0
	.end_amdhsa_kernel

amdhsa.kernels:
  - .agpr_count:     0
    .args:
      - .offset:         0
        .size:           192
        .value_kind:     by_value
      - .offset:         192
        .size:           4
        .value_kind:     hidden_block_count_x
      - .offset:         196
        .size:           4
        .value_kind:     hidden_block_count_y
      - .offset:         200
        .size:           4
        .value_kind:     hidden_block_count_z
      - .offset:         204
        .size:           2
        .value_kind:     hidden_group_size_x
      - .offset:         206
        .size:           2
        .value_kind:     hidden_group_size_y
      - .offset:         208
        .size:           2
        .value_kind:     hidden_group_size_z
      - .offset:         210
        .size:           2
        .value_kind:     hidden_remainder_x
      - .offset:         212
        .size:           2
        .value_kind:     hidden_remainder_y
      - .offset:         214
        .size:           2
        .value_kind:     hidden_remainder_z
      - .offset:         232
        .size:           8
        .value_kind:     hidden_global_offset_x
      - .offset:         240
        .size:           8
        .value_kind:     hidden_global_offset_y
      - .offset:         248
        .size:           8
        .value_kind:     hidden_global_offset_z
      - .offset:         256
        .size:           2
        .value_kind:     hidden_grid_dims
      - .offset:         280
        .size:           8
        .value_kind:     hidden_multigrid_sync_arg
      - .offset:         312
        .size:           4
        .value_kind:     hidden_dynamic_lds_size
    .group_segment_fixed_size: 0
    .kernarg_segment_align: 8
    .kernarg_segment_size: 448
    .language:       OpenCL C
    .language_version:
      - 2
      - 0
    .max_flat_workgroup_size: 512
    .name:           _Z9trunk_fwd4Args
    .private_segment_fixed_size: 0
    .sgpr_count:     108
    .sgpr_spill_count: 123
    .symbol:         _Z9trunk_fwd4Args.kd
    .uniform_work_group_size: 1
    .uses_dynamic_stack: false
    .vgpr_count:     255
    .vgpr_spill_count: 0
    .wavefront_size: 64
